# hyena step-1 staging: second chunk/sequence row loads issued together with the first (one memory round trip instead of two per channel), both lengths
# baseline (speedup 1.0000x reference)
.LBB0_490:
	s_add_i32 s0, s48, 0x800
	s_ashr_i32 s1, s0, 31
	s_lshl_b64 s[50:51], s[0:1], 16
	s_add_u32 s50, s87, s50
	s_addc_u32 s51, s90, s51
	s_lshl_b64 s[0:1], s[0:1], 2
	s_add_u32 s62, s20, s0
	s_addc_u32 s63, s21, s1
	s_ashr_i32 s49, s48, 31
	s_lshl_b64 s[60:61], s[48:49], 2
	s_add_u32 s49, s20, s60
	s_addc_u32 s60, s21, s61
	s_add_u32 s64, s49, 0x5000
	s_addc_u32 s65, s60, 0
	s_add_u32 s66, s49, 0x8000
	s_addc_u32 s67, s60, 0
	v_mov_b32_e32 v210, v204
	s_add_u32 s68, s22, s0
	s_movk_i32 s0, 0x400
	s_addc_u32 s69, s23, s1
	v_cmp_gt_i32_e32 vcc, s0, v210
	s_and_saveexec_b64 s[0:1], vcc
	s_cbranch_execz .LBB0_497
	global_load_dword v10, v205, s[66:67]
	global_load_dword v12, v205, s[68:69]
	global_load_dword v14, v205, s[64:65]
	global_load_dword v15, v205, s[62:63]
	v_lshl_add_u32 v18, v210, 6, 0
	v_lshlrev_b32_e32 v16, 4, v210
	s_mov_b64 s[70:71], 0
	v_mov_b32_e32 v30, v210
	s_mov_b32 s98, 0
	s_branch .LBB0_493
.Lmy_hy1_p2:
	v_mov_b32_e32 v2, v40
	v_mov_b32_e32 v3, v41
	v_mov_b32_e32 v4, v42
	v_mov_b32_e32 v5, v43
	v_mov_b32_e32 v6, v44
	v_mov_b32_e32 v7, v45
	v_mov_b32_e32 v8, v46
	v_mov_b32_e32 v9, v47
	v_mov_b32_e32 v27, v48
	v_mov_b32_e32 v25, v49
	s_mov_b64 s[72:73], exec

.LBB0_493:
	s_cmp_lg_u32 s98, 0
	s_cbranch_scc1 .Lmy_hy1_p2
	s_mov_b32 s98, 1
	v_ashrrev_i32_e32 v17, 31, v16
	v_lshl_add_u64 v[28:29], v[16:17], 1, s[50:51]
	global_load_dwordx4 v[2:5], v[28:29], off offset:16 nt
	global_load_dwordx4 v[6:9], v[28:29], off nt
	v_add_co_u32_e32 v50, vcc, 0x4000, v28
	s_nop 1
	v_addc_co_u32_e32 v51, vcc, 0, v29, vcc
	global_load_dwordx4 v[40:43], v[50:51], off offset:16 nt
	global_load_dwordx4 v[44:47], v[50:51], off nt
	global_load_ushort v48, v[50:51], off offset:-2
	v_mov_b32_e32 v49, 0
	v_cmp_ne_u32_e32 vcc, 0x1ff, v30
	s_and_saveexec_b64 s[72:73], vcc
	global_load_ushort v49, v[50:51], off offset:32
	s_or_b64 exec, exec, s[72:73]
	v_cmp_lt_i32_e32 vcc, 0, v30
	v_mov_b32_e32 v25, 0
	v_mov_b32_e32 v27, 0
	s_and_saveexec_b64 s[72:73], vcc
	s_cbranch_execz .LBB0_495
	v_mov_b32_e32 v17, v205
	v_lshl_add_u64 v[26:27], v[16:17], 1, s[50:51]
	global_load_ushort v27, v[26:27], off offset:-2

.LBB0_522:
	v_ashrrev_i32_e32 v25, 31, v24
	v_lshl_add_u64 v[30:31], v[24:25], 1, s[70:71]
	global_load_dwordx4 v[2:5], v[30:31], off offset:16 nt
	global_load_dwordx4 v[6:9], v[30:31], off nt
	v_lshlrev_b32_e32 v50, 5, v210
	v_add_u32_e32 v50, 0xc000, v50
	global_load_dwordx4 v[40:43], v50, s[50:51] offset:16 nt
	global_load_dwordx4 v[44:47], v50, s[50:51] nt
	v_mov_b32_e32 v48, 0
	v_mov_b32_e32 v49, 0
	v_cmp_lt_i32_e32 vcc, 0, v210
	s_and_saveexec_b64 s[64:65], vcc
	global_load_ushort v48, v50, s[50:51] offset:-2
	s_or_b64 exec, exec, s[64:65]
	v_cmp_ne_u32_e32 vcc, 0x1ff, v210
	s_and_saveexec_b64 s[64:65], vcc
	global_load_ushort v49, v50, s[50:51] offset:32
	s_or_b64 exec, exec, s[64:65]
	v_add_u32_e32 v33, 0x200, v26
	v_cmp_lt_i32_e32 vcc, 0, v33
	v_mov_b32_e32 v27, 0
	v_mov_b32_e32 v29, 0
	s_and_saveexec_b64 s[64:65], vcc
	s_cbranch_execz .LBB0_524
	v_mov_b32_e32 v25, v205
	v_lshl_add_u64 v[28:29], v[24:25], 1, s[70:71]
	global_load_ushort v29, v[28:29], off offset:-2

.LBB0_528:
	v_mov_b32_e32 v2, v40
	v_mov_b32_e32 v3, v41
	v_mov_b32_e32 v4, v42
	v_mov_b32_e32 v5, v43
	v_mov_b32_e32 v6, v44
	v_mov_b32_e32 v7, v45
	v_mov_b32_e32 v8, v46
	v_mov_b32_e32 v9, v47
	v_mov_b32_e32 v27, v48
	v_mov_b32_e32 v25, v49
	v_add_u32_e32 v32, 0x200, v18
	s_mov_b64 s[64:65], exec
	s_branch .LBB0_527
